# job1 MFMA/VALU interleave: second key block exp2, row-sum adds, later fragment conversions and l update ride in the gaps of the eight PV MFMAs
# baseline (speedup 1.0000x reference)
.LBB0_1168:
	v_exp_f32_e32 v34, v34
	v_exp_f32_e32 v35, v35
	v_exp_f32_e32 v36, v36
	v_exp_f32_e32 v37, v37
	v_exp_f32_e32 v38, v38
	v_exp_f32_e32 v39, v39
	v_exp_f32_e32 v40, v40
	v_exp_f32_e32 v41, v41
	v_exp_f32_e32 v131, v46
	v_exp_f32_e32 v129, v47
	v_exp_f32_e32 v132, v48
	v_exp_f32_e32 v133, v49
	v_cvt_pk_bf16_f32 v46, v34, v35
	v_cvt_pk_bf16_f32 v47, v36, v37
	v_cvt_pk_bf16_f32 v48, v38, v39
	v_cvt_pk_bf16_f32 v49, v40, v41
	v_exp_f32_e32 v42, v42
	v_exp_f32_e32 v43, v43
	v_exp_f32_e32 v44, v44
	v_exp_f32_e32 v45, v45
	v_add_f32_e32 v134, v34, v35
	v_add_f32_e32 v134, v36, v134
	v_add_f32_e32 v134, v37, v134
	v_add_f32_e32 v134, v38, v134
	v_add_f32_e32 v134, v39, v134
	v_add_f32_e32 v134, v40, v134
	v_add_f32_e32 v134, v41, v134
	s_waitcnt lgkmcnt(0)
	v_mfma_f32_32x32x16_bf16 v[2:17], v[136:139], v[46:49], v[2:17]
	v_add_f32_e32 v134, v42, v134
	v_add_f32_e32 v134, v43, v134
	v_add_f32_e32 v134, v44, v134
	v_add_f32_e32 v134, v45, v134
	v_cvt_pk_bf16_f32 v42, v42, v43
	v_cvt_pk_bf16_f32 v43, v44, v45
	v_mfma_f32_32x32x16_bf16 v[18:33], v[140:143], v[46:49], v[18:33]
	v_add_f32_e32 v134, v131, v134
	v_add_f32_e32 v134, v129, v134
	v_add_f32_e32 v134, v132, v134
	v_add_f32_e32 v134, v133, v134
	v_cvt_pk_bf16_f32 v44, v131, v129
	v_cvt_pk_bf16_f32 v45, v132, v133
	v_exp_f32_e32 v50, v50
	v_exp_f32_e32 v51, v51
	v_mfma_f32_32x32x16_bf16 v[2:17], v[144:147], v[42:45], v[2:17]
	v_exp_f32_e32 v52, v52
	v_exp_f32_e32 v53, v53
	v_exp_f32_e32 v54, v54
	v_exp_f32_e32 v55, v55
	v_add_f32_e32 v134, v50, v134
	v_add_f32_e32 v134, v51, v134
	v_mfma_f32_32x32x16_bf16 v[18:33], v[148:151], v[42:45], v[18:33]
	v_exp_f32_e32 v56, v56
	v_exp_f32_e32 v57, v57
	v_add_f32_e32 v134, v52, v134
	v_add_f32_e32 v134, v53, v134
	v_cvt_pk_bf16_f32 v38, v50, v51
	v_cvt_pk_bf16_f32 v39, v52, v53
	v_add_f32_e32 v134, v54, v134
	v_add_f32_e32 v134, v55, v134
	v_add_f32_e32 v134, v56, v134
	v_add_f32_e32 v134, v57, v134
	v_cvt_pk_bf16_f32 v40, v54, v55
	v_cvt_pk_bf16_f32 v41, v56, v57
	v_exp_f32_e32 v58, v58
	v_exp_f32_e32 v59, v59
	v_mfma_f32_32x32x16_bf16 v[2:17], v[152:155], v[38:41], v[2:17]
	v_exp_f32_e32 v60, v60
	v_exp_f32_e32 v61, v61
	v_exp_f32_e32 v62, v62
	v_exp_f32_e32 v63, v63
	v_add_f32_e32 v134, v58, v134
	v_add_f32_e32 v134, v59, v134
	v_mfma_f32_32x32x16_bf16 v[18:33], v[156:159], v[38:41], v[18:33]
	v_exp_f32_e32 v64, v64
	v_exp_f32_e32 v65, v65
	v_add_f32_e32 v134, v60, v134
	v_add_f32_e32 v134, v61, v134
	v_add_f32_e32 v134, v62, v134
	v_add_f32_e32 v134, v63, v134
	v_add_f32_e32 v134, v64, v134
	v_add_f32_e32 v134, v65, v134
	v_cvt_pk_bf16_f32 v34, v58, v59
	v_cvt_pk_bf16_f32 v35, v60, v61
	v_cvt_pk_bf16_f32 v36, v62, v63
	v_cvt_pk_bf16_f32 v37, v64, v65
	v_fmac_f32_e32 v134, v128, v120
	v_mov_b32_e32 v128, v134
	v_mfma_f32_32x32x16_bf16 v[2:17], v[160:163], v[34:37], v[2:17]
	v_mfma_f32_32x32x16_bf16 v[18:33], v[164:167], v[34:37], v[18:33]
	s_branch .LBB0_1170

.LBB0_1182:
	v_exp_f32_e32 v34, v34
	v_exp_f32_e32 v35, v35
	v_exp_f32_e32 v36, v36
	v_exp_f32_e32 v37, v37
	v_exp_f32_e32 v38, v38
	v_exp_f32_e32 v39, v39
	v_exp_f32_e32 v40, v40
	v_exp_f32_e32 v41, v41
	v_exp_f32_e32 v131, v46
	v_exp_f32_e32 v130, v47
	v_exp_f32_e32 v132, v48
	v_exp_f32_e32 v133, v49
	v_cvt_pk_bf16_f32 v46, v34, v35
	v_cvt_pk_bf16_f32 v47, v36, v37
	v_cvt_pk_bf16_f32 v48, v38, v39
	v_cvt_pk_bf16_f32 v49, v40, v41
	v_exp_f32_e32 v42, v42
	v_exp_f32_e32 v43, v43
	v_exp_f32_e32 v44, v44
	v_exp_f32_e32 v45, v45
	v_add_f32_e32 v134, v34, v35
	v_add_f32_e32 v134, v36, v134
	v_add_f32_e32 v134, v37, v134
	v_add_f32_e32 v134, v38, v134
	v_add_f32_e32 v134, v39, v134
	v_add_f32_e32 v134, v40, v134
	v_add_f32_e32 v134, v41, v134
	s_waitcnt lgkmcnt(0)
	v_mfma_f32_32x32x16_bf16 v[2:17], v[136:139], v[46:49], v[2:17]
	v_add_f32_e32 v134, v42, v134
	v_add_f32_e32 v134, v43, v134
	v_add_f32_e32 v134, v44, v134
	v_add_f32_e32 v134, v45, v134
	v_cvt_pk_bf16_f32 v42, v42, v43
	v_cvt_pk_bf16_f32 v43, v44, v45
	v_mfma_f32_32x32x16_bf16 v[18:33], v[140:143], v[46:49], v[18:33]
	v_add_f32_e32 v134, v131, v134
	v_add_f32_e32 v134, v130, v134
	v_add_f32_e32 v134, v132, v134
	v_add_f32_e32 v134, v133, v134
	v_cvt_pk_bf16_f32 v44, v131, v130
	v_cvt_pk_bf16_f32 v45, v132, v133
	v_exp_f32_e32 v50, v50
	v_exp_f32_e32 v51, v51
	v_mfma_f32_32x32x16_bf16 v[2:17], v[144:147], v[42:45], v[2:17]
	v_exp_f32_e32 v52, v52
	v_exp_f32_e32 v53, v53
	v_exp_f32_e32 v54, v54
	v_exp_f32_e32 v55, v55
	v_add_f32_e32 v134, v50, v134
	v_add_f32_e32 v134, v51, v134
	v_mfma_f32_32x32x16_bf16 v[18:33], v[148:151], v[42:45], v[18:33]
	v_exp_f32_e32 v56, v56
	v_exp_f32_e32 v57, v57
	v_add_f32_e32 v134, v52, v134
	v_add_f32_e32 v134, v53, v134
	v_cvt_pk_bf16_f32 v38, v50, v51
	v_cvt_pk_bf16_f32 v39, v52, v53
	v_add_f32_e32 v134, v54, v134
	v_add_f32_e32 v134, v55, v134
	v_add_f32_e32 v134, v56, v134
	v_add_f32_e32 v134, v57, v134
	v_cvt_pk_bf16_f32 v40, v54, v55
	v_cvt_pk_bf16_f32 v41, v56, v57
	v_exp_f32_e32 v58, v58
	v_exp_f32_e32 v59, v59
	v_mfma_f32_32x32x16_bf16 v[2:17], v[152:155], v[38:41], v[2:17]
	v_exp_f32_e32 v60, v60
	v_exp_f32_e32 v61, v61
	v_exp_f32_e32 v62, v62
	v_exp_f32_e32 v63, v63
	v_add_f32_e32 v134, v58, v134
	v_add_f32_e32 v134, v59, v134
	v_mfma_f32_32x32x16_bf16 v[18:33], v[156:159], v[38:41], v[18:33]
	v_exp_f32_e32 v64, v64
	v_exp_f32_e32 v65, v65
	v_add_f32_e32 v134, v60, v134
	v_add_f32_e32 v134, v61, v134
	v_add_f32_e32 v134, v62, v134
	v_add_f32_e32 v134, v63, v134
	v_add_f32_e32 v134, v64, v134
	v_add_f32_e32 v134, v65, v134
	v_cvt_pk_bf16_f32 v34, v58, v59
	v_cvt_pk_bf16_f32 v35, v60, v61
	v_cvt_pk_bf16_f32 v36, v62, v63
	v_cvt_pk_bf16_f32 v37, v64, v65
	v_fmac_f32_e32 v134, v128, v120
	v_mov_b32_e32 v128, v134
	v_mfma_f32_32x32x16_bf16 v[2:17], v[160:163], v[34:37], v[2:17]
	v_mfma_f32_32x32x16_bf16 v[18:33], v[164:167], v[34:37], v[18:33]
	s_cmp_ge_u32 s44, s38
	s_cbranch_scc0 .LBB0_1185
	s_branch .LBB0_1188
